# Attention QK^T: K-fragment ds_reads double-buffered in spare VGPRs (next step's reads issued before the current step's MFMAs) in the differential, neighbourhood and dilated loops
# speedup vs baseline: 1.0112x; 1.0112x over previous
; #define LAS __attribute__((address_space(3)))
; template <int KSTEPS, class Pol>
; __device__ __forceinline__ void attn_pass(LAS unsigned char* lds, const Pol& P, const bf16_t* qb, int ldq, const bf16_t* kb, int ldk, const bf16_t* vb, int ldv,
;                                           float qs, f32x16 (&O)[4], float& m, float& l) {
;     ...
;     auto qk_softmax = [&](int st, int t) __attribute__((always_inline)) {
;         LAS unsigned char* Kb = lds + st * A_STAGE + krow;
;         f32x16 S0, S1;
;         P.fill(S0, S1, qi, half, t, wave);
; #pragma unroll
;         for (int ks = 0; ks < KSTEPS; ++ks) {
;             const int so = ((2 * ks) ^ kx) << 4;
;             const bf16x8 a0 = *(const LAS bf16x8*)(Kb + so);
;             const bf16x8 a1 = *(const LAS bf16x8*)(Kb + 32 * KROWB + so);
;             S0 = MFMA32(a0, qf[ks], S0);
;             S1 = MFMA32(a1, qf[ks], S1);
;         }
;         S0 = S0 * qs; S1 = S1 * qs;
;         float mx = fmaxf(S0[0], S1[0]);
; #pragma unroll
;         for (int i = 1; i < 16; ++i) mx = fmaxf(fmaxf(mx, S0[i]), S1[i]);
;         mx = fmaxf(mx, __shfl_xor(mx, 32));
;         const float mnew = fmaxf(m, mx);
;         const float alpha = __builtin_amdgcn_exp2f(m - mnew);
;         m = mnew;
;         {
;             const f32x2 nm = {-mnew, -mnew};
; #pragma unroll
;             for (int i = 0; i < 16; i += 2) { const f32x2 a = (f32x2){S0[i], S0[i + 1]} + nm, b = (f32x2){S1[i], S1[i + 1]} + nm; S0[i] = a.x; S0[i + 1] = a.y; S1[i] = b.x; S1[i + 1] = b.y; }
;         }
;         f32x2 ls2 = {0.f, 0.f};
; #pragma unroll
;         for (int s = 0; s < 4; ++s) {
;             unsigned w[4];
; #pragma unroll
;             for (int e = 0; e < 4; ++e) {
;                 const int i = 8 * (s & 1) + 2 * e;
;                 f32x2 pv;
;                 pv.x = __builtin_amdgcn_exp2f(s < 2 ? S0[i] : S1[i]); pv.y = __builtin_amdgcn_exp2f(s < 2 ? S0[i + 1] : S1[i + 1]);
;                 ls2 = ls2 + pv;
;                 w[e] = pk2(pv.x, pv.y);
;             }
;             u32x4 wv; wv.x = w[0]; wv.y = w[1]; wv.z = w[2]; wv.w = w[3];
;             pf[s] = __builtin_bit_cast(bf16x8, wv);
;         }
;         l = l * alpha + (ls2.x + ls2.y);
;         if (__any(alpha != 1.0f)) {
; #pragma unroll
;             for (int blk = 0; blk < 4; ++blk) O[blk] = O[blk] * alpha;
;         }
.LBB0_237:
	s_lshl_b32 s44, s74, 15
	s_add_i32 s44, s44, 0
	v_add_u32_e32 v0, s44, v160
	v_add_u32_e32 v6, v0, v161
	ds_read_b128 v[2:5], v6
	ds_read_b128 v[6:9], v6 offset:8192
	v_add_u32_e32 v200, v0, v162
	ds_read_b128 v[192:195], v200
	ds_read_b128 v[196:199], v200 offset:8192
	v_and_b32_e32 v15, 64, v234
	v_xor_b32_e32 v14, 32, v234
	v_add_u32_e32 v15, 64, v15
	s_waitcnt lgkmcnt(3)
	v_mfma_f32_32x32x16_bf16 v[96:111], v[2:5], v[112:115], v[96:111]
	v_cmp_lt_i32_e32 vcc, v14, v15
	s_nop 1
	v_cndmask_b32_e32 v14, v234, v14, vcc
	v_lshlrev_b32_e32 v14, 2, v14
	s_waitcnt lgkmcnt(2)
	v_mfma_f32_32x32x16_bf16 v[80:95], v[6:9], v[112:115], v[80:95]
	v_add_u32_e32 v6, v0, v163
	ds_read_b128 v[2:5], v6
	ds_read_b128 v[6:9], v6 offset:8192
	s_waitcnt lgkmcnt(3)
	v_mfma_f32_32x32x16_bf16 v[96:111], v[192:195], v[116:119], v[96:111]
	s_waitcnt lgkmcnt(2)
	v_mfma_f32_32x32x16_bf16 v[80:95], v[196:199], v[116:119], v[80:95]
	v_add_u32_e32 v200, v0, v164
	ds_read_b128 v[192:195], v200
	ds_read_b128 v[196:199], v200 offset:8192
	s_waitcnt lgkmcnt(3)
	v_mfma_f32_32x32x16_bf16 v[96:111], v[2:5], v[120:123], v[96:111]
	s_waitcnt lgkmcnt(2)
	v_mfma_f32_32x32x16_bf16 v[80:95], v[6:9], v[120:123], v[80:95]
	v_add_u32_e32 v6, v0, v165
	ds_read_b128 v[2:5], v6
	ds_read_b128 v[6:9], v6 offset:8192
	s_waitcnt lgkmcnt(3)
	v_mfma_f32_32x32x16_bf16 v[96:111], v[192:195], v[124:127], v[96:111]
	s_waitcnt lgkmcnt(2)
	v_mfma_f32_32x32x16_bf16 v[80:95], v[196:199], v[124:127], v[80:95]
	v_add_u32_e32 v200, v0, v166
	ds_read_b128 v[192:195], v200
	ds_read_b128 v[196:199], v200 offset:8192
	s_waitcnt lgkmcnt(3)
	v_mfma_f32_32x32x16_bf16 v[96:111], v[2:5], v[128:131], v[96:111]
	s_waitcnt lgkmcnt(2)
	v_mfma_f32_32x32x16_bf16 v[80:95], v[6:9], v[128:131], v[80:95]
	v_add_u32_e32 v6, v0, v167
	ds_read_b128 v[2:5], v6
	ds_read_b128 v[6:9], v6 offset:8192
	s_waitcnt lgkmcnt(3)
	v_mfma_f32_32x32x16_bf16 v[96:111], v[192:195], v[132:135], v[96:111]
	s_waitcnt lgkmcnt(2)
	v_mfma_f32_32x32x16_bf16 v[80:95], v[196:199], v[132:135], v[80:95]
	v_add_u32_e32 v200, v0, v168
	ds_read_b128 v[192:195], v200
	ds_read_b128 v[196:199], v200 offset:8192
	s_waitcnt lgkmcnt(3)
	v_mfma_f32_32x32x16_bf16 v[96:111], v[2:5], v[136:139], v[96:111]
	s_waitcnt lgkmcnt(2)
	v_mfma_f32_32x32x16_bf16 v[80:95], v[6:9], v[136:139], v[80:95]
	s_waitcnt lgkmcnt(1)
	v_mfma_f32_32x32x16_bf16 v[96:111], v[192:195], v[140:143], v[96:111]
	s_waitcnt lgkmcnt(0)
	v_mfma_f32_32x32x16_bf16 v[80:95], v[196:199], v[140:143], v[80:95]
	s_nop 9
	v_mul_f32_e64 v96, v96, s20
	v_mul_f32_e64 v97, v97, s20
	v_mul_f32_e64 v98, v98, s20
	v_mul_f32_e64 v99, v99, s20
	v_mul_f32_e64 v100, v100, s20
	v_mul_f32_e64 v101, v101, s20
	v_pk_mul_f32 v[12:13], v[102:103], s[20:21] op_sel_hi:[1,0]
	v_pk_mul_f32 v[8:9], v[104:105], s[20:21] op_sel_hi:[1,0]
	v_pk_mul_f32 v[6:7], v[106:107], s[20:21] op_sel_hi:[1,0]
	v_pk_mul_f32 v[4:5], v[108:109], s[20:21] op_sel_hi:[1,0]
	v_pk_mul_f32 v[80:81], v[80:81], s[20:21] op_sel_hi:[1,0]
	v_pk_mul_f32 v[82:83], v[82:83], s[20:21] op_sel_hi:[1,0]
	v_max_f32_e32 v0, v96, v80
	v_max3_f32 v0, v0, v97, v81
	v_max3_f32 v0, v0, v98, v82
	v_pk_mul_f32 v[84:85], v[84:85], s[20:21] op_sel_hi:[1,0]
	v_max3_f32 v0, v0, v99, v83
	v_max3_f32 v0, v0, v100, v84
	v_pk_mul_f32 v[86:87], v[86:87], s[20:21] op_sel_hi:[1,0]
	v_max3_f32 v0, v0, v101, v85
	v_max3_f32 v0, v0, v12, v86
	v_pk_mul_f32 v[88:89], v[88:89], s[20:21] op_sel_hi:[1,0]
	v_max3_f32 v0, v0, v13, v87
	v_max3_f32 v0, v0, v8, v88
	v_pk_mul_f32 v[90:91], v[90:91], s[20:21] op_sel_hi:[1,0]
	v_max3_f32 v0, v0, v9, v89
	v_max3_f32 v0, v0, v6, v90
	v_pk_mul_f32 v[92:93], v[92:93], s[20:21] op_sel_hi:[1,0]
	v_max3_f32 v0, v0, v7, v91
	v_max3_f32 v0, v0, v4, v92
	v_pk_mul_f32 v[2:3], v[110:111], s[20:21] op_sel_hi:[1,0]
	v_pk_mul_f32 v[10:11], v[94:95], s[20:21] op_sel_hi:[1,0]
	v_max3_f32 v0, v0, v5, v93
	v_max3_f32 v0, v0, v2, v10
	v_max3_f32 v0, v0, v3, v11
	ds_bpermute_b32 v14, v14, v0
	s_waitcnt lgkmcnt(0)
	v_max3_f32 v14, v181, v0, v14
	v_sub_f32_e32 v0, v181, v14
	v_exp_f32_e32 v0, v0
	s_nop 0
	v_cmp_neq_f32_e32 vcc, 1.0, v0
	s_cbranch_vccz .LBB0_239
	v_pk_mul_f32 v[78:79], v[78:79], v[0:1] op_sel_hi:[1,0]
	v_pk_mul_f32 v[76:77], v[76:77], v[0:1] op_sel_hi:[1,0]
	v_pk_mul_f32 v[74:75], v[74:75], v[0:1] op_sel_hi:[1,0]
	v_pk_mul_f32 v[72:73], v[72:73], v[0:1] op_sel_hi:[1,0]
	v_pk_mul_f32 v[70:71], v[70:71], v[0:1] op_sel_hi:[1,0]
	v_pk_mul_f32 v[68:69], v[68:69], v[0:1] op_sel_hi:[1,0]
	v_pk_mul_f32 v[66:67], v[66:67], v[0:1] op_sel_hi:[1,0]
	v_pk_mul_f32 v[64:65], v[64:65], v[0:1] op_sel_hi:[1,0]
	v_pk_mul_f32 v[62:63], v[62:63], v[0:1] op_sel_hi:[1,0]
	v_pk_mul_f32 v[60:61], v[60:61], v[0:1] op_sel_hi:[1,0]
	v_pk_mul_f32 v[58:59], v[58:59], v[0:1] op_sel_hi:[1,0]
	v_pk_mul_f32 v[56:57], v[56:57], v[0:1] op_sel_hi:[1,0]
	v_pk_mul_f32 v[54:55], v[54:55], v[0:1] op_sel_hi:[1,0]
	v_pk_mul_f32 v[52:53], v[52:53], v[0:1] op_sel_hi:[1,0]
	v_pk_mul_f32 v[50:51], v[50:51], v[0:1] op_sel_hi:[1,0]
	v_pk_mul_f32 v[48:49], v[48:49], v[0:1] op_sel_hi:[1,0]
	v_pk_mul_f32 v[46:47], v[46:47], v[0:1] op_sel_hi:[1,0]
	v_pk_mul_f32 v[44:45], v[44:45], v[0:1] op_sel_hi:[1,0]
	v_pk_mul_f32 v[42:43], v[42:43], v[0:1] op_sel_hi:[1,0]
	v_pk_mul_f32 v[40:41], v[40:41], v[0:1] op_sel_hi:[1,0]
	v_pk_mul_f32 v[38:39], v[38:39], v[0:1] op_sel_hi:[1,0]
	v_pk_mul_f32 v[36:37], v[36:37], v[0:1] op_sel_hi:[1,0]
	v_pk_mul_f32 v[34:35], v[34:35], v[0:1] op_sel_hi:[1,0]
	v_pk_mul_f32 v[32:33], v[32:33], v[0:1] op_sel_hi:[1,0]
	v_pk_mul_f32 v[30:31], v[30:31], v[0:1] op_sel_hi:[1,0]
	v_pk_mul_f32 v[28:29], v[28:29], v[0:1] op_sel_hi:[1,0]
	v_pk_mul_f32 v[26:27], v[26:27], v[0:1] op_sel_hi:[1,0]
	v_pk_mul_f32 v[24:25], v[24:25], v[0:1] op_sel_hi:[1,0]
	v_pk_mul_f32 v[22:23], v[22:23], v[0:1] op_sel_hi:[1,0]
	v_pk_mul_f32 v[20:21], v[20:21], v[0:1] op_sel_hi:[1,0]
	v_pk_mul_f32 v[18:19], v[18:19], v[0:1] op_sel_hi:[1,0]
	v_pk_mul_f32 v[16:17], v[16:17], v[0:1] op_sel_hi:[1,0]

; #define LAS __attribute__((address_space(3)))
; template <int KSTEPS, class Pol>
; __device__ __forceinline__ void attn_pass(LAS unsigned char* lds, const Pol& P, const bf16_t* qb, int ldq, const bf16_t* kb, int ldk, const bf16_t* vb, int ldv,
;                                           float qs, f32x16 (&O)[4], float& m, float& l) {
;     ...
;         for (int ks = 0; ks < KSTEPS; ++ks) {
;             const int so = ((2 * ks) ^ kx) << 4;
;             const bf16x8 a0 = *(const LAS bf16x8*)(Kb + so);
;             const bf16x8 a1 = *(const LAS bf16x8*)(Kb + 32 * KROWB + so);
;     __device__ __forceinline__ float bias(int qi, int half, int t, int jc) const {
;         const int j = jc + 4 * half;
;         const int r = R + (qi >> 6), c = qi & 63, kr = kr_lo + t, c0 = min(max(c - 8, 0), 48);
;         const bool ok = (j >= c0) && (j < c0 + 16);
;         const int idx = min(max((kr - r + 7) * 31 + (j - c + 15), 0), 15 * 31 - 1);
;         const float bv = rpb[idx];
;         return ok ? bv : -__builtin_inff();
;     }
;     __device__ __forceinline__ void fill(f32x16& S0, f32x16& S1, int qi, int half, int t, int) const {
; #pragma unroll
;         for (int i = 0; i < 16; ++i) { const int jc = 8 * (i >> 2) + (i & 3); S0[i] = bias(qi, half, t, jc); S1[i] = bias(qi, half, t, 32 + jc); }
.LBB0_463:
	s_add_i32 s51, s42, s49
	s_cmp_lt_u32 s51, s46
	s_cselect_b64 vcc, -1, 0
	s_cmp_gt_u32 s51, s47
	s_cselect_b64 s[52:53], -1, 0
	s_or_b64 s[52:53], vcc, s[52:53]
	s_and_b64 vcc, exec, s[52:53]
	s_cbranch_vccnz .LBB0_467
	v_subrev_u32_e32 v2, 59, v172
	v_subrev_u32_e32 v3, 27, v172
	v_subrev_u32_e32 v4, 58, v172
	v_subrev_u32_e32 v5, 26, v172
	v_subrev_u32_e32 v6, 57, v172
	v_subrev_u32_e32 v7, 25, v172
	v_subrev_u32_e32 v8, 56, v172
	v_subrev_u32_e32 v9, 24, v172
	v_med3_i32 v2, v2, 0, v239
	s_add_i32 vcc_lo, 0, 0x18000
	v_med3_i32 v3, v3, 0, v239
	v_med3_i32 v4, v4, 0, v239
	v_med3_i32 v5, v5, 0, v239
	v_med3_i32 v6, v6, 0, v239
	v_med3_i32 v7, v7, 0, v239
	v_med3_i32 v8, v8, 0, v239
	v_med3_i32 v9, v9, 0, v239
	v_readlane_b32 s52, v250, 1
	v_lshl_add_u32 v2, v2, 2, vcc_lo
	v_lshl_add_u32 v3, v3, 2, vcc_lo
	v_lshl_add_u32 v4, v4, 2, vcc_lo
	v_lshl_add_u32 v5, v5, 2, vcc_lo
	v_lshl_add_u32 v6, v6, 2, vcc_lo
	v_lshl_add_u32 v7, v7, 2, vcc_lo
	v_lshl_add_u32 v8, v8, 2, vcc_lo
	v_lshl_add_u32 v9, v9, 2, vcc_lo
	v_readlane_b32 s53, v250, 2
	ds_read_b32 v2, v2
	ds_read_b32 v3, v3
	ds_read_b32 v4, v4
	ds_read_b32 v5, v5
	ds_read_b32 v6, v6
	ds_read_b32 v7, v7
	ds_read_b32 v8, v8
	ds_read_b32 v9, v9
	s_waitcnt lgkmcnt(6)
	v_cndmask_b32_e64 v80, v238, v3, s[52:53]
	v_readlane_b32 s52, v250, 3
	v_readlane_b32 s53, v250, 4
	v_cndmask_b32_e64 v96, v2, v238, s[36:37]
	v_subrev_u32_e32 v2, 51, v172
	s_waitcnt lgkmcnt(5)
	v_cndmask_b32_e64 v97, v4, v238, s[52:53]
	v_readlane_b32 s52, v250, 5
	v_readlane_b32 s53, v250, 6
	v_subrev_u32_e32 v3, 19, v172
	v_subrev_u32_e32 v4, 50, v172
	s_waitcnt lgkmcnt(4)
	v_cndmask_b32_e64 v81, v238, v5, s[52:53]
	v_readlane_b32 s52, v250, 7
	v_readlane_b32 s53, v250, 8
	v_subrev_u32_e32 v5, 18, v172
	v_med3_i32 v2, v2, 0, v239
	s_waitcnt lgkmcnt(3)
	v_cndmask_b32_e64 v98, v6, v238, s[52:53]
	v_readlane_b32 s52, v250, 9
	v_readlane_b32 s53, v250, 10
	v_subrev_u32_e32 v6, 49, v172
	v_med3_i32 v3, v3, 0, v239
	s_waitcnt lgkmcnt(2)
	v_cndmask_b32_e64 v82, v238, v7, s[52:53]
	v_readlane_b32 s52, v250, 11
	v_readlane_b32 s53, v250, 12
	v_subrev_u32_e32 v7, 17, v172
	v_med3_i32 v4, v4, 0, v239
	s_waitcnt lgkmcnt(1)
	v_cndmask_b32_e64 v99, v8, v238, s[52:53]
	v_readlane_b32 s52, v250, 13
	v_readlane_b32 s53, v250, 14
	v_subrev_u32_e32 v8, 48, v172
	v_med3_i32 v5, v5, 0, v239
	s_waitcnt lgkmcnt(0)
	v_cndmask_b32_e64 v83, v238, v9, s[52:53]
	v_add_u32_e32 v9, -16, v172
	v_med3_i32 v6, v6, 0, v239
	v_med3_i32 v7, v7, 0, v239
	v_med3_i32 v8, v8, 0, v239
	v_med3_i32 v9, v9, 0, v239
	v_lshl_add_u32 v2, v2, 2, vcc_lo
	v_lshl_add_u32 v3, v3, 2, vcc_lo
	v_lshl_add_u32 v4, v4, 2, vcc_lo
	v_lshl_add_u32 v5, v5, 2, vcc_lo
	v_lshl_add_u32 v6, v6, 2, vcc_lo
	v_lshl_add_u32 v7, v7, 2, vcc_lo
	v_lshl_add_u32 v8, v8, 2, vcc_lo
	v_lshl_add_u32 v9, v9, 2, vcc_lo
	ds_read_b32 v2, v2
	ds_read_b32 v3, v3
	ds_read_b32 v4, v4
	ds_read_b32 v5, v5
	ds_read_b32 v6, v6
	ds_read_b32 v7, v7
	ds_read_b32 v8, v8
	ds_read_b32 v9, v9
	v_readlane_b32 s52, v250, 15
	v_readlane_b32 s53, v250, 16
	s_waitcnt lgkmcnt(6)
	v_cndmask_b32_e64 v84, v238, v3, s[54:55]
	s_waitcnt lgkmcnt(5)
	v_cndmask_b32_e64 v101, v4, v238, s[56:57]
	v_cndmask_b32_e64 v100, v2, v238, s[52:53]
	s_waitcnt lgkmcnt(4)
	v_cndmask_b32_e64 v85, v238, v5, s[58:59]
	s_waitcnt lgkmcnt(3)
	v_cndmask_b32_e64 v102, v6, v238, s[60:61]
	v_subrev_u32_e32 v2, 43, v172
	v_add_u32_e32 v3, -11, v172
	v_subrev_u32_e32 v4, 42, v172
	v_add_u32_e32 v5, -10, v172
	v_subrev_u32_e32 v6, 41, v172
	s_waitcnt lgkmcnt(2)
	v_cndmask_b32_e64 v86, v238, v7, s[62:63]
	s_waitcnt lgkmcnt(1)
	v_cndmask_b32_e64 v103, v8, v238, s[64:65]
	s_waitcnt lgkmcnt(0)
	v_cndmask_b32_e64 v87, v238, v9, s[40:41]
	v_med3_i32 v2, v2, 0, v239
	v_med3_i32 v3, v3, 0, v239
	v_med3_i32 v4, v4, 0, v239
	v_med3_i32 v5, v5, 0, v239
	v_med3_i32 v6, v6, 0, v239
	v_add_u32_e32 v7, -9, v172
	v_subrev_u32_e32 v8, 40, v172
	v_add_u32_e32 v9, -8, v172
	v_lshl_add_u32 v2, v2, 2, vcc_lo
	v_lshl_add_u32 v3, v3, 2, vcc_lo
	v_lshl_add_u32 v4, v4, 2, vcc_lo
	v_lshl_add_u32 v5, v5, 2, vcc_lo
	v_lshl_add_u32 v6, v6, 2, vcc_lo
	v_med3_i32 v7, v7, 0, v239
	v_med3_i32 v8, v8, 0, v239
	v_med3_i32 v9, v9, 0, v239
	v_lshl_add_u32 v7, v7, 2, vcc_lo
	v_lshl_add_u32 v8, v8, 2, vcc_lo
	v_lshl_add_u32 v9, v9, 2, vcc_lo
	ds_read_b32 v2, v2
	ds_read_b32 v3, v3
	ds_read_b32 v4, v4
	ds_read_b32 v10, v5
	ds_read_b32 v5, v6
	ds_read_b32 v11, v7
	ds_read_b32 v6, v8
	ds_read_b32 v12, v9
	s_waitcnt lgkmcnt(7)
	v_cndmask_b32_e64 v104, v238, v2, s[68:69]
	v_subrev_u32_e32 v2, 35, v172
	v_med3_i32 v2, v2, 0, v239
	s_waitcnt lgkmcnt(1)
	v_cndmask_b32_e64 v107, v238, v6, s[80:81]
	v_lshl_add_u32 v6, v2, 2, vcc_lo
	v_add_u32_e32 v2, -3, v172
	v_med3_i32 v2, v2, 0, v239
	v_lshl_add_u32 v7, v2, 2, vcc_lo
	v_subrev_u32_e32 v2, 34, v172
	v_med3_i32 v2, v2, 0, v239
	v_lshl_add_u32 v8, v2, 2, vcc_lo
	v_add_u32_e32 v2, -2, v172
	v_med3_i32 v2, v2, 0, v239
	v_lshl_add_u32 v9, v2, 2, vcc_lo
	v_subrev_u32_e32 v2, 33, v172
	v_med3_i32 v2, v2, 0, v239
	v_lshl_add_u32 v13, v2, 2, vcc_lo
	v_add_u32_e32 v2, -1, v172
	s_lshl_b32 s51, s50, 15
	v_med3_i32 v2, v2, 0, v239
	s_add_i32 s51, s51, 0
	v_lshl_add_u32 v14, v2, 2, vcc_lo
	v_subrev_u32_e32 v2, 32, v172
	v_add_u32_e32 v0, s51, v145
	v_med3_i32 v2, v2, 0, v239
	v_lshl_add_u32 v15, v2, 2, vcc_lo
	v_med3_i32 v2, v172, 0, v239
	v_add_u32_e32 v90, v0, v156
	v_cndmask_b32_e64 v88, v238, v3, s[70:71]
	v_cndmask_b32_e64 v105, v238, v4, s[72:73]
	v_cndmask_b32_e64 v106, v238, v5, s[76:77]
	v_lshl_add_u32 v89, v2, 2, vcc_lo
	ds_read_b128 v[2:5], v90
	ds_read_b32 v6, v6
	ds_read_b32 v92, v7
	ds_read_b32 v7, v8
	ds_read_b32 v93, v9
	ds_read_b32 v8, v13
	ds_read_b32 v13, v14
	ds_read_b32 v9, v15
	ds_read_b32 v14, v89
	s_waitcnt lgkmcnt(7)
; #define LAS __attribute__((address_space(3)))
; __device__ __forceinline__ unsigned pk2(float lo, float hi) { f32x2 v = {lo, hi}; bf16x2_t b = __builtin_convertvector(v, bf16x2_t); return __builtin_bit_cast(unsigned, b); }
; #define MFMA32(a, b, c) __builtin_amdgcn_mfma_f32_32x32x16_bf16((a), (b), (c), 0, 0, 0)
; template <int KSTEPS, class Pol>
; __device__ __forceinline__ void attn_pass(LAS unsigned char* lds, const Pol& P, const bf16_t* qb, int ldq, const bf16_t* kb, int ldk, const bf16_t* vb, int ldv,
;                                           float qs, f32x16 (&O)[4], float& m, float& l) {
;     ...
;         for (int ks = 0; ks < KSTEPS; ++ks) {
;             const int so = ((2 * ks) ^ kx) << 4;
;             const bf16x8 a0 = *(const LAS bf16x8*)(Kb + so);
;             const bf16x8 a1 = *(const LAS bf16x8*)(Kb + 32 * KROWB + so);
;             S0 = MFMA32(a0, qf[ks], S0);
;             S1 = MFMA32(a1, qf[ks], S1);
;         }
;         S0 = S0 * qs; S1 = S1 * qs;
;         float mx = fmaxf(S0[0], S1[0]);
; #pragma unroll
;         for (int i = 1; i < 16; ++i) mx = fmaxf(fmaxf(mx, S0[i]), S1[i]);
;         mx = fmaxf(mx, __shfl_xor(mx, 32));
;         const float mnew = fmaxf(m, mx);
;         const float alpha = __builtin_amdgcn_exp2f(m - mnew);
;         m = mnew;
;         {
;             const f32x2 nm = {-mnew, -mnew};
; #pragma unroll
;             for (int i = 0; i < 16; i += 2) { const f32x2 a = (f32x2){S0[i], S0[i + 1]} + nm, b = (f32x2){S1[i], S1[i + 1]} + nm; S0[i] = a.x; S0[i + 1] = a.y; S1[i] = b.x; S1[i + 1] = b.y; }
;         }
;         f32x2 ls2 = {0.f, 0.f};
; #pragma unroll
;         for (int s = 0; s < 4; ++s) {
;             unsigned w[4];
; #pragma unroll
;             for (int e = 0; e < 4; ++e) {
;                 const int i = 8 * (s & 1) + 2 * e;
;                 f32x2 pv;
;                 pv.x = __builtin_amdgcn_exp2f(s < 2 ? S0[i] : S1[i]); pv.y = __builtin_amdgcn_exp2f(s < 2 ? S0[i + 1] : S1[i + 1]);
;                 ls2 = ls2 + pv;
;                 w[e] = pk2(pv.x, pv.y);
;             }
;             u32x4 wv; wv.x = w[0]; wv.y = w[1]; wv.z = w[2]; wv.w = w[3];
;             pf[s] = __builtin_bit_cast(bf16x8, wv);
;         }
;         l = l * alpha + (ls2.x + ls2.y);
;         if (__any(alpha != 1.0f)) {
; #pragma unroll
;             for (int blk = 0; blk < 4; ++blk) O[blk] = O[blk] * alpha;
;         }
	v_cndmask_b32_e64 v108, v238, v6, s[84:85]
	s_waitcnt lgkmcnt(5)
	v_cndmask_b32_e64 v109, v238, v7, s[88:89]
	s_waitcnt lgkmcnt(3)
	v_cndmask_b32_e64 v110, v238, v8, s[92:93]
	s_waitcnt lgkmcnt(1)
	v_cndmask_b32_e64 v111, v238, v9, s[96:97]
	ds_read_b128 v[6:9], v90 offset:8192
	v_cndmask_b32_e64 v89, v238, v10, s[74:75]
	v_cndmask_b32_e64 v90, v238, v11, s[78:79]
	v_cndmask_b32_e64 v91, v238, v12, s[82:83]
	v_cndmask_b32_e64 v92, v238, v92, s[86:87]
	v_cndmask_b32_e64 v93, v238, v93, s[90:91]
	v_cndmask_b32_e64 v94, v238, v13, s[94:95]
	s_waitcnt lgkmcnt(1)
	v_cndmask_b32_e64 v95, v238, v14, s[2:3]
	v_mfma_f32_32x32x16_bf16 v[96:111], v[2:5], v[112:115], v[96:111]
	v_and_b32_e32 v15, 64, v234
	v_xor_b32_e32 v14, 32, v234
	v_add_u32_e32 v15, 64, v15
	v_cmp_lt_i32_e32 vcc, v14, v15
	s_nop 1
	v_cndmask_b32_e32 v14, v234, v14, vcc
	s_waitcnt lgkmcnt(0)
	v_mfma_f32_32x32x16_bf16 v[80:95], v[6:9], v[112:115], v[80:95]
	v_add_u32_e32 v6, v0, v157
	ds_read_b128 v[2:5], v6
	ds_read_b128 v[6:9], v6 offset:8192
	v_add_u32_e32 v200, v0, v158
	ds_read_b128 v[192:195], v200
	ds_read_b128 v[196:199], v200 offset:8192
	v_lshlrev_b32_e32 v14, 2, v14
	s_waitcnt lgkmcnt(3)
	v_mfma_f32_32x32x16_bf16 v[96:111], v[2:5], v[116:119], v[96:111]
	s_waitcnt lgkmcnt(2)
	v_mfma_f32_32x32x16_bf16 v[80:95], v[6:9], v[116:119], v[80:95]
	v_add_u32_e32 v6, v0, v159
	ds_read_b128 v[2:5], v6
	ds_read_b128 v[6:9], v6 offset:8192
	s_waitcnt lgkmcnt(3)
	v_mfma_f32_32x32x16_bf16 v[96:111], v[192:195], v[120:123], v[96:111]
	s_waitcnt lgkmcnt(2)
	v_mfma_f32_32x32x16_bf16 v[80:95], v[196:199], v[120:123], v[80:95]
	v_add_u32_e32 v200, v0, v160
	ds_read_b128 v[192:195], v200
	ds_read_b128 v[196:199], v200 offset:8192
	s_waitcnt lgkmcnt(3)
	v_mfma_f32_32x32x16_bf16 v[96:111], v[2:5], v[124:127], v[96:111]
	s_waitcnt lgkmcnt(2)
	v_mfma_f32_32x32x16_bf16 v[80:95], v[6:9], v[124:127], v[80:95]
	v_add_u32_e32 v6, v0, v161
	ds_read_b128 v[2:5], v6
	ds_read_b128 v[6:9], v6 offset:8192
	s_waitcnt lgkmcnt(3)
	v_mfma_f32_32x32x16_bf16 v[96:111], v[192:195], v[128:131], v[96:111]
	s_waitcnt lgkmcnt(2)
	v_mfma_f32_32x32x16_bf16 v[80:95], v[196:199], v[128:131], v[80:95]
	v_add_u32_e32 v200, v0, v162
	ds_read_b128 v[192:195], v200
	ds_read_b128 v[196:199], v200 offset:8192
	s_waitcnt lgkmcnt(3)
	v_mfma_f32_32x32x16_bf16 v[96:111], v[2:5], v[132:135], v[96:111]
	s_waitcnt lgkmcnt(2)
	v_mfma_f32_32x32x16_bf16 v[80:95], v[6:9], v[132:135], v[80:95]
	v_add_u32_e32 v201, v0, v163
	ds_read_b128 v[2:5], v201
	ds_read_b128 v[6:9], v201 offset:8192
	s_waitcnt lgkmcnt(3)
	v_mfma_f32_32x32x16_bf16 v[96:111], v[192:195], v[136:139], v[96:111]
	s_waitcnt lgkmcnt(2)
	v_mfma_f32_32x32x16_bf16 v[80:95], v[196:199], v[136:139], v[80:95]
	s_waitcnt lgkmcnt(1)
	v_mfma_f32_32x32x16_bf16 v[96:111], v[2:5], v[140:143], v[96:111]
	s_waitcnt lgkmcnt(0)
	v_mfma_f32_32x32x16_bf16 v[80:95], v[6:9], v[140:143], v[80:95]
	s_nop 9
	v_mul_f32_e64 v96, v96, s20
	v_mul_f32_e64 v97, v97, s20
	v_mul_f32_e64 v98, v98, s20
	v_mul_f32_e64 v99, v99, s20
	v_mul_f32_e64 v100, v100, s20
	v_mul_f32_e64 v101, v101, s20
	v_pk_mul_f32 v[102:103], v[102:103], s[20:21] op_sel_hi:[1,0]
	v_pk_mul_f32 v[10:11], v[104:105], s[20:21] op_sel_hi:[1,0]
	v_pk_mul_f32 v[6:7], v[106:107], s[20:21] op_sel_hi:[1,0]
	v_pk_mul_f32 v[4:5], v[108:109], s[20:21] op_sel_hi:[1,0]
	v_pk_mul_f32 v[80:81], v[80:81], s[20:21] op_sel_hi:[1,0]
	v_pk_mul_f32 v[82:83], v[82:83], s[20:21] op_sel_hi:[1,0]
	v_max_f32_e32 v0, v96, v80
	v_max3_f32 v0, v0, v97, v81
	v_max3_f32 v0, v0, v98, v82
	v_pk_mul_f32 v[84:85], v[84:85], s[20:21] op_sel_hi:[1,0]
	v_max3_f32 v0, v0, v99, v83
	v_max3_f32 v0, v0, v100, v84
	v_pk_mul_f32 v[86:87], v[86:87], s[20:21] op_sel_hi:[1,0]
	v_max3_f32 v0, v0, v101, v85
	v_max3_f32 v0, v0, v102, v86
	v_pk_mul_f32 v[88:89], v[88:89], s[20:21] op_sel_hi:[1,0]
	v_max3_f32 v0, v0, v103, v87
	v_max3_f32 v0, v0, v10, v88
	v_pk_mul_f32 v[90:91], v[90:91], s[20:21] op_sel_hi:[1,0]
	v_max3_f32 v0, v0, v11, v89
	v_max3_f32 v0, v0, v6, v90
	v_pk_mul_f32 v[12:13], v[92:93], s[20:21] op_sel_hi:[1,0]
	v_max3_f32 v0, v0, v7, v91
	v_max3_f32 v0, v0, v4, v12
	v_pk_mul_f32 v[2:3], v[110:111], s[20:21] op_sel_hi:[1,0]
	v_pk_mul_f32 v[8:9], v[94:95], s[20:21] op_sel_hi:[1,0]
	v_max3_f32 v0, v0, v5, v13
	v_max3_f32 v0, v0, v2, v8
	v_max3_f32 v0, v0, v3, v9
	ds_bpermute_b32 v14, v14, v0
	s_waitcnt lgkmcnt(0)
	v_max3_f32 v0, v175, v0, v14
	v_sub_f32_e32 v14, v175, v0
	v_exp_f32_e32 v14, v14
	s_nop 0
	v_cmp_neq_f32_e32 vcc, 1.0, v14
	s_cbranch_vccz .LBB0_466
	v_pk_mul_f32 v[78:79], v[78:79], v[14:15] op_sel_hi:[1,0]
	v_pk_mul_f32 v[76:77], v[76:77], v[14:15] op_sel_hi:[1,0]
	v_pk_mul_f32 v[74:75], v[74:75], v[14:15] op_sel_hi:[1,0]
	v_pk_mul_f32 v[72:73], v[72:73], v[14:15] op_sel_hi:[1,0]
	v_pk_mul_f32 v[70:71], v[70:71], v[14:15] op_sel_hi:[1,0]
	v_pk_mul_f32 v[68:69], v[68:69], v[14:15] op_sel_hi:[1,0]
	v_pk_mul_f32 v[66:67], v[66:67], v[14:15] op_sel_hi:[1,0]
	v_pk_mul_f32 v[64:65], v[64:65], v[14:15] op_sel_hi:[1,0]
	v_pk_mul_f32 v[62:63], v[62:63], v[14:15] op_sel_hi:[1,0]
	v_pk_mul_f32 v[60:61], v[60:61], v[14:15] op_sel_hi:[1,0]
	v_pk_mul_f32 v[58:59], v[58:59], v[14:15] op_sel_hi:[1,0]
	v_pk_mul_f32 v[56:57], v[56:57], v[14:15] op_sel_hi:[1,0]
	v_pk_mul_f32 v[54:55], v[54:55], v[14:15] op_sel_hi:[1,0]
	v_pk_mul_f32 v[52:53], v[52:53], v[14:15] op_sel_hi:[1,0]
	v_pk_mul_f32 v[50:51], v[50:51], v[14:15] op_sel_hi:[1,0]
	v_pk_mul_f32 v[48:49], v[48:49], v[14:15] op_sel_hi:[1,0]
	v_pk_mul_f32 v[46:47], v[46:47], v[14:15] op_sel_hi:[1,0]
	v_pk_mul_f32 v[44:45], v[44:45], v[14:15] op_sel_hi:[1,0]
	v_pk_mul_f32 v[42:43], v[42:43], v[14:15] op_sel_hi:[1,0]
	v_pk_mul_f32 v[40:41], v[40:41], v[14:15] op_sel_hi:[1,0]
	v_pk_mul_f32 v[38:39], v[38:39], v[14:15] op_sel_hi:[1,0]
	v_pk_mul_f32 v[36:37], v[36:37], v[14:15] op_sel_hi:[1,0]
	v_pk_mul_f32 v[34:35], v[34:35], v[14:15] op_sel_hi:[1,0]
	v_pk_mul_f32 v[32:33], v[32:33], v[14:15] op_sel_hi:[1,0]
	v_pk_mul_f32 v[30:31], v[30:31], v[14:15] op_sel_hi:[1,0]
	v_pk_mul_f32 v[28:29], v[28:29], v[14:15] op_sel_hi:[1,0]
	v_pk_mul_f32 v[26:27], v[26:27], v[14:15] op_sel_hi:[1,0]
	v_pk_mul_f32 v[24:25], v[24:25], v[14:15] op_sel_hi:[1,0]
	v_pk_mul_f32 v[22:23], v[22:23], v[14:15] op_sel_hi:[1,0]
	v_pk_mul_f32 v[20:21], v[20:21], v[14:15] op_sel_hi:[1,0]
	v_pk_mul_f32 v[18:19], v[18:19], v[14:15] op_sel_hi:[1,0]
	v_pk_mul_f32 v[16:17], v[16:17], v[14:15] op_sel_hi:[1,0]

; #define LAS __attribute__((address_space(3)))
; template <int KSTEPS, class Pol>
; __device__ __forceinline__ void attn_pass(LAS unsigned char* lds, const Pol& P, const bf16_t* qb, int ldq, const bf16_t* kb, int ldk, const bf16_t* vb, int ldv,
;                                           float qs, f32x16 (&O)[4], float& m, float& l) {
;     ...
;     auto qk_softmax = [&](int st, int t) __attribute__((always_inline)) {
;         LAS unsigned char* Kb = lds + st * A_STAGE + krow;
;         f32x16 S0, S1;
;         P.fill(S0, S1, qi, half, t, wave);
; #pragma unroll
;         for (int ks = 0; ks < KSTEPS; ++ks) {
;             const int so = ((2 * ks) ^ kx) << 4;
;             const bf16x8 a0 = *(const LAS bf16x8*)(Kb + so);
;             const bf16x8 a1 = *(const LAS bf16x8*)(Kb + 32 * KROWB + so);
;             S0 = MFMA32(a0, qf[ks], S0);
;             S1 = MFMA32(a1, qf[ks], S1);
;         }
;         S0 = S0 * qs; S1 = S1 * qs;
;         float mx = fmaxf(S0[0], S1[0]);
; #pragma unroll
;         for (int i = 1; i < 16; ++i) mx = fmaxf(fmaxf(mx, S0[i]), S1[i]);
;         mx = fmaxf(mx, __shfl_xor(mx, 32));
;         const float mnew = fmaxf(m, mx);
;         const float alpha = __builtin_amdgcn_exp2f(m - mnew);
;         m = mnew;
;         {
;             const f32x2 nm = {-mnew, -mnew};
; #pragma unroll
;             for (int i = 0; i < 16; i += 2) { const f32x2 a = (f32x2){S0[i], S0[i + 1]} + nm, b = (f32x2){S1[i], S1[i + 1]} + nm; S0[i] = a.x; S0[i + 1] = a.y; S1[i] = b.x; S1[i + 1] = b.y; }
;         }
;         f32x2 ls2 = {0.f, 0.f};
; #pragma unroll
;         for (int s = 0; s < 4; ++s) {
;             unsigned w[4];
; #pragma unroll
;             for (int e = 0; e < 4; ++e) {
;                 const int i = 8 * (s & 1) + 2 * e;
;                 f32x2 pv;
;                 pv.x = __builtin_amdgcn_exp2f(s < 2 ? S0[i] : S1[i]); pv.y = __builtin_amdgcn_exp2f(s < 2 ? S0[i + 1] : S1[i + 1]);
;                 ls2 = ls2 + pv;
;                 w[e] = pk2(pv.x, pv.y);
;             }
;             u32x4 wv; wv.x = w[0]; wv.y = w[1]; wv.z = w[2]; wv.w = w[3];
;             pf[s] = __builtin_bit_cast(bf16x8, wv);
;         }
;         l = l * alpha + (ls2.x + ls2.y);
;         if (__any(alpha != 1.0f)) {
; #pragma unroll
;             for (int blk = 0; blk < 4; ++blk) O[blk] = O[blk] * alpha;
;         }
.LBB0_505:
	s_add_i32 s36, s51, 0
	v_add_u32_e32 v0, s36, v151
	v_add_u32_e32 v6, v0, v152
	ds_read_b128 v[2:5], v6
	ds_read_b128 v[6:9], v6 offset:4096
	v_add_u32_e32 v200, v0, v153
	ds_read_b128 v[192:195], v200
	ds_read_b128 v[196:199], v200 offset:4096
	s_mov_b32 s40, 0x3e38aa3b
	s_waitcnt lgkmcnt(3)
	v_mfma_f32_32x32x16_bf16 v[80:95], v[2:5], v[112:115], v[80:95]
	s_waitcnt lgkmcnt(2)
	v_mfma_f32_32x32x16_bf16 v[96:111], v[6:9], v[112:115], v[96:111]
	v_add_u32_e32 v6, v0, v155
	ds_read_b128 v[2:5], v6
	ds_read_b128 v[6:9], v6 offset:4096
	s_waitcnt lgkmcnt(3)
	v_mfma_f32_32x32x16_bf16 v[80:95], v[192:195], v[116:119], v[80:95]
	s_waitcnt lgkmcnt(2)
	v_mfma_f32_32x32x16_bf16 v[96:111], v[196:199], v[116:119], v[96:111]
	v_add_u32_e32 v200, v0, v156
	ds_read_b128 v[192:195], v200
	ds_read_b128 v[196:199], v200 offset:4096
	s_waitcnt lgkmcnt(3)
	v_mfma_f32_32x32x16_bf16 v[80:95], v[2:5], v[120:123], v[80:95]
	s_waitcnt lgkmcnt(2)
	v_mfma_f32_32x32x16_bf16 v[96:111], v[6:9], v[120:123], v[96:111]
	s_waitcnt lgkmcnt(1)
	v_mfma_f32_32x32x16_bf16 v[80:95], v[192:195], v[124:127], v[80:95]
	s_waitcnt lgkmcnt(0)
	v_mfma_f32_32x32x16_bf16 v[96:111], v[196:199], v[124:127], v[96:111]
	s_nop 9
	v_mul_f32_e64 v14, v80, s40
	v_mul_f32_e64 v15, v81, s40
	v_mul_f32_e64 v12, v82, s40
	v_mul_f32_e64 v13, v83, s40
	v_mul_f32_e64 v142, v94, s40
	v_mul_f32_e64 v143, v95, s40
	v_pk_mul_f32 v[10:11], v[84:85], s[40:41] op_sel_hi:[1,0]
	v_pk_mul_f32 v[144:145], v[92:93], s[40:41] op_sel_hi:[1,0]
	v_pk_mul_f32 v[8:9], v[86:87], s[40:41] op_sel_hi:[1,0]
	v_pk_mul_f32 v[146:147], v[88:89], s[40:41] op_sel_hi:[1,0]
	v_pk_mul_f32 v[96:97], v[96:97], s[40:41] op_sel_hi:[1,0]
	v_pk_mul_f32 v[98:99], v[98:99], s[40:41] op_sel_hi:[1,0]
	v_max_f32_e32 v0, v14, v96
	v_max3_f32 v0, v0, v15, v97
	v_max3_f32 v0, v0, v12, v98
	v_pk_mul_f32 v[94:95], v[100:101], s[40:41] op_sel_hi:[1,0]
	v_max3_f32 v0, v0, v13, v99
	v_max3_f32 v0, v0, v10, v94
	v_pk_mul_f32 v[92:93], v[102:103], s[40:41] op_sel_hi:[1,0]
	v_max3_f32 v0, v0, v11, v95
	v_max3_f32 v0, v0, v8, v92
	v_pk_mul_f32 v[88:89], v[104:105], s[40:41] op_sel_hi:[1,0]
	v_max3_f32 v0, v0, v9, v93
	v_max3_f32 v0, v0, v146, v88
	v_pk_mul_f32 v[90:91], v[90:91], s[40:41] op_sel_hi:[1,0]
	v_pk_mul_f32 v[86:87], v[106:107], s[40:41] op_sel_hi:[1,0]
	v_max3_f32 v0, v0, v147, v89
	v_max3_f32 v0, v0, v90, v86
	v_pk_mul_f32 v[4:5], v[108:109], s[40:41] op_sel_hi:[1,0]
	v_max3_f32 v0, v0, v91, v87
	v_max3_f32 v0, v0, v144, v4
	v_pk_mul_f32 v[2:3], v[110:111], s[40:41] op_sel_hi:[1,0]
	v_max3_f32 v0, v0, v145, v5
	v_max3_f32 v0, v0, v142, v2
	v_max3_f32 v0, v0, v143, v3
	ds_bpermute_b32 v6, v148, v0
	s_waitcnt lgkmcnt(0)
	v_max3_f32 v0, v167, v0, v6
	v_sub_f32_e32 v6, v167, v0
	v_exp_f32_e32 v6, v6
	s_nop 0
	v_cmp_neq_f32_e32 vcc, 1.0, v6
	s_cbranch_vccz .LBB0_507
	v_pk_mul_f32 v[78:79], v[78:79], v[6:7] op_sel_hi:[1,0]
	v_pk_mul_f32 v[76:77], v[76:77], v[6:7] op_sel_hi:[1,0]
	v_pk_mul_f32 v[74:75], v[74:75], v[6:7] op_sel_hi:[1,0]
	v_pk_mul_f32 v[72:73], v[72:73], v[6:7] op_sel_hi:[1,0]
	v_pk_mul_f32 v[70:71], v[70:71], v[6:7] op_sel_hi:[1,0]
	v_pk_mul_f32 v[68:69], v[68:69], v[6:7] op_sel_hi:[1,0]
	v_pk_mul_f32 v[66:67], v[66:67], v[6:7] op_sel_hi:[1,0]
	v_pk_mul_f32 v[64:65], v[64:65], v[6:7] op_sel_hi:[1,0]
	v_pk_mul_f32 v[62:63], v[62:63], v[6:7] op_sel_hi:[1,0]
	v_pk_mul_f32 v[60:61], v[60:61], v[6:7] op_sel_hi:[1,0]
	v_pk_mul_f32 v[58:59], v[58:59], v[6:7] op_sel_hi:[1,0]
	v_pk_mul_f32 v[56:57], v[56:57], v[6:7] op_sel_hi:[1,0]
	v_pk_mul_f32 v[54:55], v[54:55], v[6:7] op_sel_hi:[1,0]
	v_pk_mul_f32 v[52:53], v[52:53], v[6:7] op_sel_hi:[1,0]
	v_pk_mul_f32 v[50:51], v[50:51], v[6:7] op_sel_hi:[1,0]
	v_pk_mul_f32 v[48:49], v[48:49], v[6:7] op_sel_hi:[1,0]
	v_pk_mul_f32 v[46:47], v[46:47], v[6:7] op_sel_hi:[1,0]
	v_pk_mul_f32 v[44:45], v[44:45], v[6:7] op_sel_hi:[1,0]
	v_pk_mul_f32 v[42:43], v[42:43], v[6:7] op_sel_hi:[1,0]
	v_pk_mul_f32 v[40:41], v[40:41], v[6:7] op_sel_hi:[1,0]
	v_pk_mul_f32 v[38:39], v[38:39], v[6:7] op_sel_hi:[1,0]
	v_pk_mul_f32 v[36:37], v[36:37], v[6:7] op_sel_hi:[1,0]
	v_pk_mul_f32 v[34:35], v[34:35], v[6:7] op_sel_hi:[1,0]
	v_pk_mul_f32 v[32:33], v[32:33], v[6:7] op_sel_hi:[1,0]
	v_pk_mul_f32 v[30:31], v[30:31], v[6:7] op_sel_hi:[1,0]
	v_pk_mul_f32 v[28:29], v[28:29], v[6:7] op_sel_hi:[1,0]
	v_pk_mul_f32 v[26:27], v[26:27], v[6:7] op_sel_hi:[1,0]
	v_pk_mul_f32 v[24:25], v[24:25], v[6:7] op_sel_hi:[1,0]
	v_pk_mul_f32 v[22:23], v[22:23], v[6:7] op_sel_hi:[1,0]
	v_pk_mul_f32 v[20:21], v[20:21], v[6:7] op_sel_hi:[1,0]
	v_pk_mul_f32 v[18:19], v[18:19], v[6:7] op_sel_hi:[1,0]
	v_pk_mul_f32 v[16:17], v[16:17], v[6:7] op_sel_hi:[1,0]
